# MLA long block first + LN1 layer1 loads batched
# speedup vs baseline: 1.0061x; 1.0061x over previous
; template <int DQK, bool BIAS, class Loader>
; __device__ __forceinline__ void attn_unit(const int tid, LAS unsigned char* lds, Loader& L, const bf16_t* qptr, bool wave_active, int t0, int t1, int wt0, int wt1, int nkeys, int qpos, int kpos0, bf16_t* optr) {
;     constexpr int NKS = DQK / 16, KSTR = DQK * 2 + 16;
;     const int lane = tid & 63, l31 = lane & 31, hi = lane >> 5;
;     bf16x8 qf[NKS];
; #pragma unroll
;     for (int ks = 0; ks < NKS; ++ks) qf[ks] = *(const bf16x8*)(qptr + ks * 16 + hi * 8);
;     f32x16 o0, o1, o2, o3;
; #pragma unroll
;     for (int r = 0; r < 16; ++r) { o0[r] = 0.f; o1[r] = 0.f; o2[r] = 0.f; o3[r] = 0.f; }
;     float m_run = -1e30f, l_run = 0.f;
;     L.load(t0); L.store(lds, lds + AT_VBUF0); if (t0 + 1 < t1) L.load(t0 + 1); __syncthreads();
; __global__ void __launch_bounds__(512, 2) hse_fwd(Params P) {
;     ...
;                     for (int pass = 0; pass < 2; ++pass) { const int qb = (pass & 1) == 0 ? x : 31 - x; const int rr = bl * TT + qb * 256 + wave * 32 + l31; const int cw = 4 * qb + (wave >> 1);
;                         attn_unit<192, false, MlaLoader>(tid, lds, L, qbuf + (size_t)rr * 1536 + h * 192, true, 0, 4 * qb + 4, 0, cw + 1, TT, 0, 0, ocat + (size_t)rr * 3072 + h * 128); }
.LBB0_4927:
	s_xor_b64 s[58:59], s[14:15], -1
	s_and_b64 s[14:15], s[14:15], exec
	s_cselect_b32 s18, s86, s65
	v_lshl_add_u32 v206, s18, 8, v187
	s_movk_i32 s14, 0xc00
	v_mad_i64_i32 v[0:1], s[14:15], v206, s14, v[202:203]
	s_waitcnt vmcnt(45)
	v_mov_b32_e32 v16, v184
	global_load_dwordx4 v[156:159], v[0:1], off
	global_load_dwordx4 v[152:155], v[0:1], off offset:32
	global_load_dwordx4 v[148:151], v[0:1], off offset:64
	global_load_dwordx4 v[144:147], v[0:1], off offset:96
	global_load_dwordx4 v[140:143], v[0:1], off offset:128
	global_load_dwordx4 v[136:139], v[0:1], off offset:160
	global_load_dwordx4 v[132:135], v[0:1], off offset:192
	global_load_dwordx4 v[128:131], v[0:1], off offset:224
	global_load_dwordx4 v[124:127], v[0:1], off offset:256
	global_load_dwordx4 v[120:123], v[0:1], off offset:288
	global_load_dwordx4 v[116:119], v[0:1], off offset:320
	global_load_dwordx4 v[112:115], v[0:1], off offset:352
	v_mov_b32_e32 v20, v184
	v_lshlrev_b32_e32 v4, 4, v16
	v_lshlrev_b32_e32 v0, 7, v16
	v_and_b32_e32 v1, 0xf0, v4
	v_lshrrev_b32_e32 v9, 3, v16
	v_and_or_b32 v0, v0, s3, v1
	s_waitcnt vmcnt(56)
	v_and_b32_e32 v17, 0x70, v4
	v_mul_lo_u32 v9, v9, s21
	v_add_u32_e32 v8, 0x10000, v0
	v_or_b32_e32 v12, v9, v17
	global_load_dwordx4 v[0:3], v0, s[48:49]
	s_nop 0
	global_load_dwordx4 v[4:7], v4, s[50:51]
	s_nop 0
	global_load_dwordx4 v[8:11], v8, s[48:49]
	s_nop 0
	global_load_dwordx4 v[12:15], v12, s[52:53]
	v_add_u32_e32 v16, 0x200, v16
	v_lshrrev_b32_e32 v16, 3, v16
	v_mul_lo_u32 v16, v16, s21
	v_or_b32_e32 v16, v16, v17
	global_load_dwordx4 v[16:19], v16, s[52:53]
	s_waitcnt vmcnt(58)
	v_mov_b32_e32 v23, v184
	v_lshlrev_b32_e32 v21, 4, v20
	s_waitcnt vmcnt(57)
	v_lshrrev_b32_e32 v24, 4, v20
	v_add_u32_e32 v22, 0x200, v20
	s_waitcnt vmcnt(55)
	v_lshrrev_b32_e32 v26, 3, v20
	v_and_b32_e32 v20, 0xf0, v21
	v_lshrrev_b32_e32 v27, 4, v22
	v_and_b32_e32 v21, 0x70, v21
	v_lshrrev_b32_e32 v25, 3, v22
	v_add_u32_e32 v20, 0, v20
	v_mul_lo_u32 v28, v26, s33
	v_add_u32_e32 v22, 0, v21
	s_waitcnt vmcnt(54)
	v_mul_lo_u32 v29, v25, s33
	v_mad_u64_u32 v[24:25], s[14:15], v24, s64, v[20:21]
	v_mad_u64_u32 v[20:21], s[14:15], v27, s64, v[20:21]
	v_mad_u64_u32 v[26:27], s[14:15], v26, s64, v[22:23]
	v_add3_u32 v21, v22, v28, s2
	v_add3_u32 v22, v22, v29, s2
	s_waitcnt vmcnt(52)
	v_mov_b32_e32 v33, v32
	v_mov_b32_e32 v46, v32
	s_waitcnt vmcnt(43)
	v_mov_b32_e32 v47, v32
	s_lshl_b32 s14, s18, 2
	v_mov_b32_e32 v34, v32
	v_mov_b32_e32 v35, v32
	v_mov_b32_e32 v36, v32
	v_mov_b32_e32 v37, v32
	v_mov_b32_e32 v38, v32
	v_mov_b32_e32 v39, v32
	v_mov_b32_e32 v40, v32
	v_mov_b32_e32 v41, v32
	v_mov_b32_e32 v42, v32
	v_mov_b32_e32 v43, v32
	v_mov_b32_e32 v44, v32
	v_mov_b32_e32 v45, v32
	v_mov_b64_e32 v[78:79], v[46:47]
	s_waitcnt vmcnt(35)
	v_mov_b64_e32 v[62:63], v[46:47]
	s_add_i32 s15, s14, s76
	s_add_i32 s26, s14, 4
	s_or_b32 s14, s14, 3
	s_mov_b32 s87, 0
	v_mov_b32_e32 v215, 0
	v_mov_b32_e32 v216, 0xf149f2ca
	s_mov_b64 s[18:19], s[30:31]
	s_mov_b64 s[60:61], s[16:17]
	s_mov_b64 s[62:63], s[0:1]
	v_mov_b64_e32 v[76:77], v[44:45]
	v_mov_b64_e32 v[74:75], v[42:43]
	v_mov_b64_e32 v[72:73], v[40:41]
	v_mov_b64_e32 v[70:71], v[38:39]
	v_mov_b64_e32 v[68:69], v[36:37]
	v_mov_b64_e32 v[66:67], v[34:35]
	v_mov_b64_e32 v[64:65], v[32:33]
	v_mov_b64_e32 v[60:61], v[44:45]
	v_mov_b64_e32 v[58:59], v[42:43]
	v_mov_b64_e32 v[56:57], v[40:41]
	v_mov_b64_e32 v[54:55], v[38:39]
	v_mov_b64_e32 v[52:53], v[36:37]
	v_mov_b64_e32 v[50:51], v[34:35]
	s_waitcnt vmcnt(4)
	ds_write_b128 v24, v[0:3]
	s_waitcnt vmcnt(2)
	ds_write_b128 v20, v[8:11]
	ds_write_b128 v26, v[4:7] offset:256
	s_waitcnt vmcnt(1)
	ds_write2_b64 v21, v[12:13], v[14:15] offset1:1
	s_waitcnt vmcnt(0)
	ds_write2_b64 v22, v[16:17], v[18:19] offset1:1
	v_mov_b64_e32 v[48:49], v[32:33]
	v_lshlrev_b32_e32 v1, 4, v23
	v_lshlrev_b32_e32 v0, 7, v23
	v_add_u32_e32 v3, 0x200, v23
	v_and_b32_e32 v4, 0xf0, v1
	v_lshrrev_b32_e32 v2, 3, v23
	v_lshrrev_b32_e32 v3, 3, v3
	v_and_or_b32 v0, v0, s3, v4
	v_and_b32_e32 v5, 0x70, v1
	v_mul_lo_u32 v2, v2, s21
	v_mul_lo_u32 v3, v3, s21
	v_add_u32_e32 v4, 0x10000, v0
	v_or_b32_e32 v2, v2, v5
	global_load_dwordx4 v[160:163], v0, s[54:55]
	global_load_dwordx4 v[168:171], v1, s[56:57]
	v_or_b32_e32 v0, v3, v5
	global_load_dwordx4 v[164:167], v4, s[54:55]
	global_load_dwordx4 v[172:175], v2, s[52:53] offset:128
	global_load_dwordx4 v[176:179], v0, s[52:53] offset:128
	v_mov_b64_e32 v[16:17], v[32:33]
	v_mov_b64_e32 v[0:1], v[32:33]
	v_mov_b64_e32 v[18:19], v[34:35]
	v_mov_b64_e32 v[20:21], v[36:37]
	v_mov_b64_e32 v[22:23], v[38:39]
	v_mov_b64_e32 v[24:25], v[40:41]
	v_mov_b64_e32 v[26:27], v[42:43]
	v_mov_b64_e32 v[28:29], v[44:45]
	v_mov_b64_e32 v[30:31], v[46:47]
	v_mov_b64_e32 v[2:3], v[34:35]
	v_mov_b64_e32 v[4:5], v[36:37]
	v_mov_b64_e32 v[6:7], v[38:39]
	v_mov_b64_e32 v[8:9], v[40:41]
	v_mov_b64_e32 v[10:11], v[42:43]
	v_mov_b64_e32 v[12:13], v[44:45]
	v_mov_b64_e32 v[14:15], v[46:47]
	s_waitcnt lgkmcnt(0)
	s_barrier
	s_branch .LBB0_4930

; __device__ __forceinline__ float bf_lo(unsigned w) { return __uint_as_float(w << 16); }
; __device__ __forceinline__ float bf_hi(unsigned w) { return __uint_as_float(w & 0xffff0000u); }
; #define INP(k) pt.in(k)
; __global__ void __launch_bounds__(512, 2) hse_fwd(Params P) {
;     ...
;         for (int ar = bid * 8 + wave; ar < MX; ar += G * 8) { bf16_t* xr = xbuf + (size_t)ar * DM; f32x4 v[8]; float s = 0.f;
;             const float* xs = ar < MP ? INP(0) + (size_t)ar * DM : INP(1) + (size_t)(ar - MP) * DM; const bf16_t* vb = hbuf + (size_t)ar * DM; const int st = row_stream(ar); const float* a = adal + (size_t)st * NADA;
; #pragma unroll
;             for (int i = 0; i < 8; ++i) { f32x4 x; if (l == 0) x = *(const f32x4*)(xs + i * 256 + lane * 4); else { const u32x2 xw = *(const u32x2*)(xr + i * 256 + lane * 4); x = (f32x4){bf_lo(xw.x), bf_hi(xw.x), bf_lo(xw.y), bf_hi(xw.y)}; }
;                 const u32x2 w = *(const u32x2*)(vb + i * 256 + lane * 4);
;                 v[i] = x * ALPHA + (f32x4){bf_lo(w.x), bf_hi(w.x), bf_lo(w.y), bf_hi(w.y)}; s += (v[i][0] + v[i][1]) + (v[i][2] + v[i][3]); }
.LBB0_5393:
	v_readlane_b32 s100, v255, 30
	s_waitcnt vmcnt(7)
	s_cmp_eq_u32 s100, 0
	s_cbranch_scc1 .Lf1_x0
	v_lshlrev_b32_e32 v130, 16, v132
	v_and_b32_e32 v131, 0xffff0000, v132
	v_lshlrev_b32_e32 v132, 16, v133
	v_and_b32_e32 v133, 0xffff0000, v133
.Lf1_x0:
	v_lshlrev_b32_e32 v170, 16, v166
	v_and_b32_e32 v171, 0xffff0000, v166
	v_lshlrev_b32_e32 v166, 16, v167
	v_and_b32_e32 v167, 0xffff0000, v167
	s_mov_b32 s0, 0x3fb504f3
	v_pk_fma_f32 v[186:187], v[132:133], s[0:1], v[166:167] op_sel_hi:[1,0,1]
	v_pk_fma_f32 v[188:189], v[130:131], s[0:1], v[170:171] op_sel_hi:[1,0,1]
	v_add_f32_e32 v131, v186, v187
	v_add_f32_e32 v130, v188, v189
	v_add_f32_e32 v130, v130, v131
	v_add_f32_e32 v166, 0, v130
	s_waitcnt vmcnt(6)
	s_cmp_eq_u32 s100, 0
	s_cbranch_scc1 .Lf1_x1
	v_lshlrev_b32_e32 v134, 16, v136
	v_and_b32_e32 v135, 0xffff0000, v136
	v_lshlrev_b32_e32 v136, 16, v137
	v_and_b32_e32 v137, 0xffff0000, v137
.Lf1_x1:
	v_lshlrev_b32_e32 v130, 16, v168
	v_and_b32_e32 v131, 0xffff0000, v168
	v_lshlrev_b32_e32 v132, 16, v169
	v_and_b32_e32 v133, 0xffff0000, v169
	v_pk_fma_f32 v[178:179], v[136:137], s[0:1], v[132:133] op_sel_hi:[1,0,1]
	v_pk_fma_f32 v[182:183], v[134:135], s[0:1], v[130:131] op_sel_hi:[1,0,1]
	v_add_f32_e32 v131, v178, v179
	v_add_f32_e32 v130, v182, v183
	v_add_f32_e32 v130, v130, v131
	v_add_f32_e32 v134, v166, v130
	s_waitcnt vmcnt(5)
	s_cmp_eq_u32 s100, 0
	s_cbranch_scc1 .Lf1_x2
	v_lshlrev_b32_e32 v138, 16, v140
	v_and_b32_e32 v139, 0xffff0000, v140
	v_lshlrev_b32_e32 v140, 16, v141
	v_and_b32_e32 v141, 0xffff0000, v141
.Lf1_x2:
	v_lshlrev_b32_e32 v130, 16, v172
	v_and_b32_e32 v131, 0xffff0000, v172
	v_lshlrev_b32_e32 v132, 16, v173
	v_and_b32_e32 v133, 0xffff0000, v173
	v_pk_fma_f32 v[170:171], v[140:141], s[0:1], v[132:133] op_sel_hi:[1,0,1]
	v_pk_fma_f32 v[172:173], v[138:139], s[0:1], v[130:131] op_sel_hi:[1,0,1]
	v_add_f32_e32 v131, v170, v171
	v_add_f32_e32 v130, v172, v173
	v_add_f32_e32 v130, v130, v131
	v_add_f32_e32 v134, v134, v130
	s_waitcnt vmcnt(4)
	s_cmp_eq_u32 s100, 0
	s_cbranch_scc1 .Lf1_x3
	v_lshlrev_b32_e32 v142, 16, v144
	v_and_b32_e32 v143, 0xffff0000, v144
	v_lshlrev_b32_e32 v144, 16, v145
	v_and_b32_e32 v145, 0xffff0000, v145
.Lf1_x3:
	v_lshlrev_b32_e32 v130, 16, v174
	v_and_b32_e32 v131, 0xffff0000, v174
	v_lshlrev_b32_e32 v132, 16, v175
	v_and_b32_e32 v133, 0xffff0000, v175
	v_pk_fma_f32 v[166:167], v[144:145], s[0:1], v[132:133] op_sel_hi:[1,0,1]
	v_pk_fma_f32 v[168:169], v[142:143], s[0:1], v[130:131] op_sel_hi:[1,0,1]
	v_add_f32_e32 v131, v166, v167
	v_add_f32_e32 v130, v168, v169
	v_add_f32_e32 v130, v130, v131
	v_add_f32_e32 v134, v134, v130
	s_waitcnt vmcnt(3)
	s_cmp_eq_u32 s100, 0
	s_cbranch_scc1 .Lf1_x4
	v_lshlrev_b32_e32 v146, 16, v148
	v_and_b32_e32 v147, 0xffff0000, v148
	v_lshlrev_b32_e32 v148, 16, v149
	v_and_b32_e32 v149, 0xffff0000, v149
.Lf1_x4:
	v_lshlrev_b32_e32 v130, 16, v176
	v_and_b32_e32 v131, 0xffff0000, v176
	v_lshlrev_b32_e32 v132, 16, v177
	v_and_b32_e32 v133, 0xffff0000, v177
	v_pk_fma_f32 v[142:143], v[148:149], s[0:1], v[132:133] op_sel_hi:[1,0,1]
	v_pk_fma_f32 v[144:145], v[146:147], s[0:1], v[130:131] op_sel_hi:[1,0,1]
	v_add_f32_e32 v131, v142, v143
	v_add_f32_e32 v130, v144, v145
	v_add_f32_e32 v130, v130, v131
	v_add_f32_e32 v134, v134, v130
	s_waitcnt vmcnt(2)
	s_cmp_eq_u32 s100, 0
	s_cbranch_scc1 .Lf1_x5
	v_lshlrev_b32_e32 v150, 16, v152
	v_and_b32_e32 v151, 0xffff0000, v152
	v_lshlrev_b32_e32 v152, 16, v153
	v_and_b32_e32 v153, 0xffff0000, v153
.Lf1_x5:
	v_lshlrev_b32_e32 v130, 16, v180
	v_and_b32_e32 v131, 0xffff0000, v180
	v_lshlrev_b32_e32 v132, 16, v181
	v_and_b32_e32 v133, 0xffff0000, v181
	v_pk_fma_f32 v[138:139], v[152:153], s[0:1], v[132:133] op_sel_hi:[1,0,1]
	v_pk_fma_f32 v[140:141], v[150:151], s[0:1], v[130:131] op_sel_hi:[1,0,1]
	v_add_f32_e32 v131, v138, v139
	v_add_f32_e32 v130, v140, v141
	v_add_f32_e32 v130, v130, v131
	v_add_f32_e32 v146, v134, v130
	s_waitcnt vmcnt(1)
	s_cmp_eq_u32 s100, 0
	s_cbranch_scc1 .Lf1_x6
	v_lshlrev_b32_e32 v154, 16, v156
	v_and_b32_e32 v155, 0xffff0000, v156
	v_lshlrev_b32_e32 v156, 16, v157
	v_and_b32_e32 v157, 0xffff0000, v157
.Lf1_x6:
	v_lshlrev_b32_e32 v130, 16, v184
	v_and_b32_e32 v131, 0xffff0000, v184
	v_lshlrev_b32_e32 v132, 16, v185
	v_and_b32_e32 v133, 0xffff0000, v185
	v_pk_fma_f32 v[134:135], v[156:157], s[0:1], v[132:133] op_sel_hi:[1,0,1]
	v_pk_fma_f32 v[136:137], v[154:155], s[0:1], v[130:131] op_sel_hi:[1,0,1]
	v_add_f32_e32 v131, v134, v135
	v_add_f32_e32 v130, v136, v137
	v_add_f32_e32 v130, v130, v131
	v_add_f32_e32 v146, v146, v130
	s_waitcnt vmcnt(0)
	s_cmp_eq_u32 s100, 0
	s_cbranch_scc1 .Lf1_x7
	v_lshlrev_b32_e32 v158, 16, v160
	v_and_b32_e32 v159, 0xffff0000, v160
	v_lshlrev_b32_e32 v160, 16, v161
	v_and_b32_e32 v161, 0xffff0000, v161
; __device__ __forceinline__ float bf_lo(unsigned w) { return __uint_as_float(w << 16); }
; __device__ __forceinline__ float bf_hi(unsigned w) { return __uint_as_float(w & 0xffff0000u); }
; __global__ void __launch_bounds__(512, 2) hse_fwd(Params P) {
;     ...
;                 v[i] = x * ALPHA + (f32x4){bf_lo(w.x), bf_hi(w.x), bf_lo(w.y), bf_hi(w.y)}; s += (v[i][0] + v[i][1]) + (v[i][2] + v[i][3]); }
;             if (st != cst) { cst = st;
; #pragma unroll
;                 for (int i = 0; i < 8; ++i) { const int c = i * 256 + lane * 4; sh[i] = *(const f32x4*)(a + 3 * DM + c); sc[i] = *(const f32x4*)(a + 4 * DM + c); } }
;             const float mean = wave_sum(s) * (1.0f / DM); float q = 0.f;
; #pragma unroll
;             for (int i = 0; i < 8; ++i) { const f32x4 d = v[i] - mean; q += (d[0] * d[0] + d[1] * d[1]) + (d[2] * d[2] + d[3] * d[3]); }
;             const float rstd = rsqrtf(wave_sum(q) * (1.0f / DM) + EPS);
.Lf1_x7:
	v_lshlrev_b32_e32 v132, 16, v190
	v_and_b32_e32 v133, 0xffff0000, v190
	v_lshlrev_b32_e32 v130, 16, v191
	v_and_b32_e32 v131, 0xffff0000, v191
	v_pk_fma_f32 v[130:131], v[160:161], s[0:1], v[130:131] op_sel_hi:[1,0,1]
	v_pk_fma_f32 v[132:133], v[158:159], s[0:1], v[132:133] op_sel_hi:[1,0,1]
	v_add_f32_e32 v148, v130, v131
	v_add_f32_e32 v147, v132, v133
	v_add_f32_e32 v147, v147, v148
	v_add_f32_e32 v146, v146, v147
	ds_swizzle_b32 v147, v146 offset:swizzle(SWAP,1)
	s_mov_b32 s0, 0xf7dff200
	s_mov_b32 s1, -1
	v_lshl_add_u64 v[152:153], v[164:165], 0, s[0:1]
	s_mov_b32 s0, 0xf7dff400
	s_waitcnt lgkmcnt(0)
	v_add_f32_e32 v146, v146, v147
	ds_swizzle_b32 v147, v146 offset:swizzle(SWAP,2)
	s_mov_b32 s1, -1
	v_lshl_add_u64 v[154:155], v[164:165], 0, s[0:1]
	s_mov_b32 s0, 0xf7dff600
	s_mov_b32 s1, -1
	s_waitcnt lgkmcnt(0)
	v_add_f32_e32 v146, v146, v147
	ds_swizzle_b32 v147, v146 offset:swizzle(SWAP,4)
	v_lshl_add_u64 v[156:157], v[164:165], 0, s[0:1]
	s_mov_b32 s0, 0xf7dff800
	s_mov_b32 s1, -1
	v_lshl_add_u64 v[158:159], v[164:165], 0, s[0:1]
	s_waitcnt lgkmcnt(0)
	v_add_f32_e32 v146, v146, v147
	ds_swizzle_b32 v147, v146 offset:swizzle(SWAP,8)
	s_mov_b32 s0, 0xf7dffa00
	s_mov_b32 s1, -1
	v_lshl_add_u64 v[160:161], v[164:165], 0, s[0:1]
	s_mov_b32 s0, 0x800000
	s_waitcnt lgkmcnt(0)
	v_add_f32_e32 v146, v146, v147
	ds_swizzle_b32 v147, v146 offset:swizzle(SWAP,16)
	s_waitcnt lgkmcnt(0)
	v_add_f32_e32 v146, v146, v147
	v_mov_b32_e32 v147, v146
	s_nop 1
	v_permlane32_swap_b32_e32 v146, v147
	v_add_f32_e32 v146, v146, v147
	v_fmac_f32_e32 v187, 0xba000000, v146
	v_fmac_f32_e32 v189, 0xba000000, v146
	v_fmamk_f32 v186, v146, 0xba000000, v186
	v_fmamk_f32 v188, v146, 0xba000000, v188
	v_mul_f32_e32 v147, v189, v189
	v_mul_f32_e32 v148, v187, v187
	v_fmac_f32_e32 v147, v188, v188
	v_fmac_f32_e32 v148, v186, v186
	v_fmac_f32_e32 v179, 0xba000000, v146
	v_fmac_f32_e32 v183, 0xba000000, v146
	v_add_f32_e32 v147, v147, v148
	v_fmamk_f32 v178, v146, 0xba000000, v178
	v_fmamk_f32 v182, v146, 0xba000000, v182
	v_mul_f32_e32 v148, v183, v183
	v_mul_f32_e32 v149, v179, v179
	v_fmac_f32_e32 v148, v182, v182
	v_fmac_f32_e32 v149, v178, v178
	v_add_f32_e32 v148, v148, v149
	v_fmac_f32_e32 v171, 0xba000000, v146
	v_fmac_f32_e32 v173, 0xba000000, v146
	v_add_f32_e32 v147, v147, v148
	v_fmamk_f32 v170, v146, 0xba000000, v170
	v_fmamk_f32 v172, v146, 0xba000000, v172
	v_mul_f32_e32 v148, v173, v173
	v_mul_f32_e32 v149, v171, v171
	v_fmac_f32_e32 v148, v172, v172
	v_fmac_f32_e32 v149, v170, v170
	v_add_f32_e32 v148, v148, v149
	v_fmac_f32_e32 v167, 0xba000000, v146
	v_fmac_f32_e32 v169, 0xba000000, v146
	v_add_f32_e32 v147, v147, v148
	v_fmamk_f32 v166, v146, 0xba000000, v166
	v_fmamk_f32 v168, v146, 0xba000000, v168
	v_mul_f32_e32 v148, v169, v169
	v_mul_f32_e32 v149, v167, v167
	v_fmac_f32_e32 v148, v168, v168
	v_fmac_f32_e32 v149, v166, v166
	v_add_f32_e32 v148, v148, v149
	v_fmac_f32_e32 v143, 0xba000000, v146
	v_fmac_f32_e32 v145, 0xba000000, v146
	v_add_f32_e32 v147, v147, v148
	v_fmamk_f32 v142, v146, 0xba000000, v142
	v_fmamk_f32 v144, v146, 0xba000000, v144
	v_mul_f32_e32 v148, v145, v145
	v_mul_f32_e32 v149, v143, v143
	v_fmac_f32_e32 v148, v144, v144
	v_fmac_f32_e32 v149, v142, v142
	v_add_f32_e32 v148, v148, v149
	v_fmac_f32_e32 v139, 0xba000000, v146
	v_fmac_f32_e32 v141, 0xba000000, v146
	v_add_f32_e32 v147, v147, v148
	v_fmamk_f32 v138, v146, 0xba000000, v138
	v_fmamk_f32 v140, v146, 0xba000000, v140
	v_mul_f32_e32 v148, v141, v141
	v_mul_f32_e32 v149, v139, v139
	v_fmac_f32_e32 v148, v140, v140
	v_fmac_f32_e32 v149, v138, v138
	v_add_f32_e32 v148, v148, v149
	v_fmac_f32_e32 v135, 0xba000000, v146
	v_fmac_f32_e32 v137, 0xba000000, v146
	v_add_f32_e32 v147, v147, v148
	v_fmamk_f32 v134, v146, 0xba000000, v134
	v_fmamk_f32 v136, v146, 0xba000000, v136
	v_mul_f32_e32 v148, v137, v137
	v_mul_f32_e32 v149, v135, v135
	v_fmac_f32_e32 v148, v136, v136
	v_fmac_f32_e32 v149, v134, v134
	v_add_f32_e32 v148, v148, v149
	v_fmac_f32_e32 v131, 0xba000000, v146
	v_fmac_f32_e32 v133, 0xba000000, v146
	v_add_f32_e32 v147, v147, v148
	v_fmamk_f32 v130, v146, 0xba000000, v130
	v_fmamk_f32 v132, v146, 0xba000000, v132
	v_mul_f32_e32 v146, v133, v133
	v_mul_f32_e32 v148, v131, v131
	v_fmac_f32_e32 v146, v132, v132
	v_fmac_f32_e32 v148, v130, v130
	v_add_f32_e32 v146, v146, v148
	v_add_f32_e32 v146, v147, v146
	ds_swizzle_b32 v147, v146 offset:swizzle(SWAP,1)
	s_waitcnt lgkmcnt(0)
	v_add_f32_e32 v146, v146, v147
	ds_swizzle_b32 v147, v146 offset:swizzle(SWAP,2)
	s_waitcnt lgkmcnt(0)
	v_add_f32_e32 v146, v146, v147
	ds_swizzle_b32 v147, v146 offset:swizzle(SWAP,4)
	s_waitcnt lgkmcnt(0)
	v_add_f32_e32 v146, v146, v147
	ds_swizzle_b32 v147, v146 offset:swizzle(SWAP,8)
	s_waitcnt lgkmcnt(0)
	v_add_f32_e32 v146, v146, v147
	ds_swizzle_b32 v147, v146 offset:swizzle(SWAP,16)
	s_waitcnt lgkmcnt(0)
; __device__ __forceinline__ unsigned cvt_pk_bf16(float lo, float hi) { unsigned r; asm volatile("v_cvt_pk_bf16_f32 %0, %1, %2" : "=v"(r) : "v"(lo), "v"(hi)); return r; }
; __global__ void __launch_bounds__(512, 2) hse_fwd(Params P) {
;     ...
;             const float rstd = rsqrtf(wave_sum(q) * (1.0f / DM) + EPS);
; #pragma unroll
;             for (int i = 0; i < 8; ++i) { const int c = i * 256 + lane * 4;
;                 const f32x4 y = (v[i] - mean) * rstd * gg[i] + bb[i]; *(u32x2*)(xr + c) = (u32x2){cvt_pk_bf16(y[0], y[1]), cvt_pk_bf16(y[2], y[3])};
;                 const f32x4 hh = y * (sc[i] + 1.0f) + sh[i];
;                 *(u32x2*)(hbuf + (size_t)ar * DM + c) = (u32x2){cvt_pk_bf16(hh[0], hh[1]), cvt_pk_bf16(hh[2], hh[3])}; } } }
	v_add_f32_e32 v146, v146, v147
	v_mov_b32_e32 v147, v146
	s_nop 1
	v_permlane32_swap_b32_e32 v146, v147
	v_add_f32_e32 v146, v146, v147
	v_mov_b32_e32 v147, 0x3727c5ac
	v_fmamk_f32 v146, v146, 0x3a000000, v147
	v_mul_f32_e32 v147, 0x4b800000, v146
	v_cmp_gt_f32_e32 vcc, s0, v146
	s_mov_b32 s0, 0xf7dffc00
	s_mov_b32 s1, -1
	v_cndmask_b32_e32 v146, v146, v147, vcc
	v_rsq_f32_e32 v148, v146
	v_lshl_add_u64 v[174:175], v[164:165], 0, s[0:1]
	s_mov_b32 s0, 0xf7dffe00
	s_mov_b32 s1, -1
	v_mul_f32_e32 v149, 0x45800000, v148
	v_cndmask_b32_e32 v148, v148, v149, vcc
	v_pk_mul_f32 v[176:177], v[148:149], v[188:189] op_sel_hi:[0,1]
	v_pk_mul_f32 v[180:181], v[148:149], v[186:187] op_sel_hi:[0,1]
	v_pk_fma_f32 v[180:181], v[26:27], v[180:181], v[36:37]
	v_pk_fma_f32 v[176:177], v[24:25], v[176:177], v[34:35]
	v_pk_add_f32 v[186:187], v[98:99], 1.0 op_sel_hi:[1,0]
	v_cvt_pk_bf16_f32 v184, v176, v177
	v_cvt_pk_bf16_f32 v185, v180, v181
	global_store_dwordx2 v[164:165], v[184:185], off offset:-3584
	v_pk_add_f32 v[184:185], v[100:101], 1.0 op_sel_hi:[1,0]
	v_pk_fma_f32 v[176:177], v[176:177], v[186:187], v[66:67]
	v_pk_fma_f32 v[180:181], v[180:181], v[184:185], v[68:69]
	v_cvt_pk_bf16_f32 v176, v176, v177
	v_pk_mul_f32 v[144:145], v[148:149], v[144:145] op_sel_hi:[0,1]
	v_cvt_pk_bf16_f32 v177, v180, v181
	global_store_dwordx2 v[152:153], v[176:177], off
	v_pk_mul_f32 v[152:153], v[148:149], v[182:183] op_sel_hi:[0,1]
	v_pk_mul_f32 v[176:177], v[148:149], v[178:179] op_sel_hi:[0,1]
	v_pk_fma_f32 v[176:177], v[30:31], v[176:177], v[40:41]
	v_pk_fma_f32 v[152:153], v[28:29], v[152:153], v[38:39]
	v_pk_add_f32 v[180:181], v[102:103], 1.0 op_sel_hi:[1,0]
	v_cvt_pk_bf16_f32 v178, v152, v153
	v_cvt_pk_bf16_f32 v179, v176, v177
	global_store_dwordx2 v[164:165], v[178:179], off offset:-3072
	v_pk_add_f32 v[178:179], v[104:105], 1.0 op_sel_hi:[1,0]
	v_pk_fma_f32 v[152:153], v[152:153], v[180:181], v[70:71]
	v_pk_fma_f32 v[176:177], v[176:177], v[178:179], v[72:73]
	v_cvt_pk_bf16_f32 v152, v152, v153
	v_pk_mul_f32 v[142:143], v[148:149], v[142:143] op_sel_hi:[0,1]
	v_cvt_pk_bf16_f32 v153, v176, v177
	global_store_dwordx2 v[154:155], v[152:153], off
	v_pk_mul_f32 v[152:153], v[148:149], v[172:173] op_sel_hi:[0,1]
	v_pk_mul_f32 v[154:155], v[148:149], v[170:171] op_sel_hi:[0,1]
	v_pk_fma_f32 v[154:155], v[18:19], v[154:155], v[44:45]
	v_pk_fma_f32 v[152:153], v[16:17], v[152:153], v[42:43]
	v_pk_add_f32 v[172:173], v[106:107], 1.0 op_sel_hi:[1,0]
	v_cvt_pk_bf16_f32 v170, v152, v153
	v_cvt_pk_bf16_f32 v171, v154, v155
	global_store_dwordx2 v[164:165], v[170:171], off offset:-2560
	v_pk_add_f32 v[170:171], v[108:109], 1.0 op_sel_hi:[1,0]
	v_pk_fma_f32 v[152:153], v[152:153], v[172:173], v[74:75]
	v_pk_fma_f32 v[154:155], v[154:155], v[170:171], v[76:77]
	v_cvt_pk_bf16_f32 v152, v152, v153
	v_pk_fma_f32 v[142:143], v[2:3], v[142:143], v[52:53]
	v_cvt_pk_bf16_f32 v153, v154, v155
	global_store_dwordx2 v[156:157], v[152:153], off
	v_pk_mul_f32 v[152:153], v[148:149], v[168:169] op_sel_hi:[0,1]
	v_pk_mul_f32 v[154:155], v[148:149], v[166:167] op_sel_hi:[0,1]
	v_pk_fma_f32 v[154:155], v[22:23], v[154:155], v[48:49]
	v_pk_fma_f32 v[152:153], v[20:21], v[152:153], v[46:47]
	v_pk_add_f32 v[166:167], v[110:111], 1.0 op_sel_hi:[1,0]
	v_cvt_pk_bf16_f32 v156, v152, v153
	v_cvt_pk_bf16_f32 v157, v154, v155
	global_store_dwordx2 v[164:165], v[156:157], off offset:-2048
	v_pk_add_f32 v[156:157], v[112:113], 1.0 op_sel_hi:[1,0]
	v_pk_fma_f32 v[152:153], v[152:153], v[166:167], v[78:79]
	v_pk_fma_f32 v[154:155], v[154:155], v[156:157], v[80:81]
	v_cvt_pk_bf16_f32 v152, v152, v153
	v_pk_fma_f32 v[144:145], v[0:1], v[144:145], v[50:51]
	v_cvt_pk_bf16_f32 v153, v154, v155
	global_store_dwordx2 v[158:159], v[152:153], off
	v_cvt_pk_bf16_f32 v152, v144, v145
	v_cvt_pk_bf16_f32 v153, v142, v143
	v_pk_add_f32 v[154:155], v[114:115], 1.0 op_sel_hi:[1,0]
	global_store_dwordx2 v[164:165], v[152:153], off offset:-1536
	v_pk_add_f32 v[152:153], v[116:117], 1.0 op_sel_hi:[1,0]
	v_pk_fma_f32 v[144:145], v[144:145], v[154:155], v[82:83]
	v_lshl_add_u64 v[150:151], v[164:165], 0, s[0:1]
	s_mov_b32 s0, 0xf7e00000
	v_pk_fma_f32 v[142:143], v[142:143], v[152:153], v[84:85]
	v_cvt_pk_bf16_f32 v144, v144, v145
	v_pk_mul_f32 v[140:141], v[148:149], v[140:141] op_sel_hi:[0,1]
	v_cvt_pk_bf16_f32 v145, v142, v143
	v_pk_mul_f32 v[138:139], v[148:149], v[138:139] op_sel_hi:[0,1]
	s_mov_b32 s1, -1
	global_store_dwordx2 v[160:161], v[144:145], off
	v_pk_fma_f32 v[138:139], v[14:15], v[138:139], v[56:57]
	v_pk_fma_f32 v[140:141], v[12:13], v[140:141], v[54:55]
	v_pk_add_f32 v[144:145], v[118:119], 1.0 op_sel_hi:[1,0]
	v_cvt_pk_bf16_f32 v142, v140, v141
	v_cvt_pk_bf16_f32 v143, v138, v139
	v_lshl_add_u64 v[146:147], v[164:165], 0, s[0:1]
	global_store_dwordx2 v[164:165], v[142:143], off offset:-1024
	v_pk_add_f32 v[142:143], v[120:121], 1.0 op_sel_hi:[1,0]
	v_pk_fma_f32 v[140:141], v[140:141], v[144:145], v[86:87]
	v_readlane_b32 s0, v253, 9
	v_pk_fma_f32 v[138:139], v[138:139], v[142:143], v[88:89]
	v_cvt_pk_bf16_f32 v140, v140, v141
	v_pk_mul_f32 v[136:137], v[148:149], v[136:137] op_sel_hi:[0,1]
	v_cvt_pk_bf16_f32 v141, v138, v139
	v_pk_mul_f32 v[134:135], v[148:149], v[134:135] op_sel_hi:[0,1]
	v_readlane_b32 s1, v253, 10
	global_store_dwordx2 v[174:175], v[140:141], off
	v_pk_fma_f32 v[134:135], v[10:11], v[134:135], v[60:61]
	v_pk_fma_f32 v[136:137], v[8:9], v[136:137], v[58:59]
	v_pk_add_f32 v[140:141], v[122:123], 1.0 op_sel_hi:[1,0]
	v_cvt_pk_bf16_f32 v138, v136, v137
	v_cvt_pk_bf16_f32 v139, v134, v135
	s_add_i32 s10, s10, s0
	v_readlane_b32 s0, v255, 24
	global_store_dwordx2 v[164:165], v[138:139], off offset:-512
	v_pk_add_f32 v[138:139], v[124:125], 1.0 op_sel_hi:[1,0]
	v_pk_fma_f32 v[136:137], v[136:137], v[140:141], v[90:91]
	v_readlane_b32 s1, v255, 25
	s_add_u32 s4, s4, s0
	v_pk_fma_f32 v[134:135], v[134:135], v[138:139], v[92:93]
	v_cvt_pk_bf16_f32 v136, v136, v137
	v_pk_mul_f32 v[132:133], v[148:149], v[132:133] op_sel_hi:[0,1]
	v_cvt_pk_bf16_f32 v137, v134, v135
	v_pk_mul_f32 v[130:131], v[148:149], v[130:131] op_sel_hi:[0,1]
	s_addc_u32 s5, s5, s1
	v_readlane_b32 s0, v255, 22
	global_store_dwordx2 v[150:151], v[136:137], off
	v_pk_fma_f32 v[130:131], v[6:7], v[130:131], v[64:65]
	v_pk_fma_f32 v[132:133], v[4:5], v[132:133], v[62:63]
	v_pk_add_f32 v[136:137], v[126:127], 1.0 op_sel_hi:[1,0]
	v_cvt_pk_bf16_f32 v134, v132, v133
	v_cvt_pk_bf16_f32 v135, v130, v131
	v_readlane_b32 s1, v255, 23
	global_store_dwordx2 v[164:165], v[134:135], off
	v_pk_add_f32 v[134:135], v[128:129], 1.0 op_sel_hi:[1,0]
	v_pk_fma_f32 v[132:133], v[132:133], v[136:137], v[94:95]
	s_cmp_gt_i32 s10, 0x81ff
	v_lshl_add_u64 v[164:165], v[164:165], 0, s[0:1]
	v_pk_fma_f32 v[130:131], v[130:131], v[134:135], v[96:97]
	v_cvt_pk_bf16_f32 v132, v132, v133
	s_nop 0
	v_cvt_pk_bf16_f32 v133, v130, v131
	global_store_dwordx2 v[146:147], v[132:133], off
	s_cbranch_scc1 .LBB0_5432

; __device__ __forceinline__ float bf_lo(unsigned w) { return __uint_as_float(w << 16); }
; __device__ __forceinline__ float bf_hi(unsigned w) { return __uint_as_float(w & 0xffff0000u); }
; #define INP(k) pt.in(k)
; __global__ void __launch_bounds__(512, 2) hse_fwd(Params P) {
;     ...
;             const float* xs = ar < MP ? INP(0) + (size_t)ar * DM : INP(1) + (size_t)(ar - MP) * DM; const bf16_t* vb = hbuf + (size_t)ar * DM; const int st = row_stream(ar); const float* a = adal + (size_t)st * NADA;
; #pragma unroll
;             for (int i = 0; i < 8; ++i) { f32x4 x; if (l == 0) x = *(const f32x4*)(xs + i * 256 + lane * 4); else { const u32x2 xw = *(const u32x2*)(xr + i * 256 + lane * 4); x = (f32x4){bf_lo(xw.x), bf_hi(xw.x), bf_lo(xw.y), bf_hi(xw.y)}; }
;                 const u32x2 w = *(const u32x2*)(vb + i * 256 + lane * 4);
.LBB0_5398:
	v_readlane_b32 s14, v255, 30
	v_readlane_b32 s15, v255, 31
	s_mov_b64 s[8:9], -1
	s_and_b64 vcc, exec, s[14:15]
	s_cbranch_vccz .LBB0_5400
	global_load_dwordx2 v[132:133], v[164:165], off offset:-3584
	s_mov_b64 s[8:9], 0
.LBB0_5400:
	v_lshlrev_b32_e32 v170, 2, v162
	v_mov_b32_e32 v171, v32
	s_andn2_b64 vcc, exec, s[8:9]
	v_lshl_add_u64 v[178:179], s[0:1], 0, v[170:171]
	s_cbranch_vccnz .LBB0_5402
	global_load_dwordx4 v[130:133], v[178:179], off
.LBB0_5402:
	v_add_co_u32_e32 v134, vcc, 0xf7e00000, v164
	v_readlane_b32 s8, v255, 30
	s_nop 0
	v_addc_co_u32_e32 v135, vcc, -1, v165, vcc
	global_load_dwordx2 v[166:167], v[134:135], off offset:-3584
	v_readlane_b32 s9, v255, 31
	s_andn2_b64 vcc, exec, s[8:9]
	s_nop 0
	v_cndmask_b32_e64 v134, 0, 1, s[8:9]
	v_cmp_ne_u32_e64 s[0:1], 1, v134
	s_mov_b64 s[8:9], -1
	s_cbranch_vccnz .LBB0_5404
	global_load_dwordx2 v[136:137], v[164:165], off offset:-3072
	s_mov_b64 s[8:9], 0
.LBB0_5404:
	s_andn2_b64 vcc, exec, s[8:9]
	s_cbranch_vccnz .LBB0_5406
	global_load_dwordx4 v[134:137], v[178:179], off offset:1024
.LBB0_5406:
	v_add_co_u32_e32 v138, vcc, 0xf7e00000, v164
	s_mov_b64 s[8:9], -1
	s_nop 0
	v_addc_co_u32_e32 v139, vcc, -1, v165, vcc
	global_load_dwordx2 v[168:169], v[138:139], off offset:-3072
	s_and_b64 vcc, exec, s[0:1]
	s_cbranch_vccnz .LBB0_5408
	global_load_dwordx2 v[140:141], v[164:165], off offset:-2560
	s_mov_b64 s[8:9], 0
.LBB0_5408:
	s_andn2_b64 vcc, exec, s[8:9]
	s_cbranch_vccnz .LBB0_5410
	global_load_dwordx4 v[138:141], v[178:179], off offset:2048
.LBB0_5410:
	v_add_co_u32_e32 v142, vcc, 0xf7e00000, v164
	s_mov_b64 s[8:9], -1
	s_nop 0
	v_addc_co_u32_e32 v143, vcc, -1, v165, vcc
	global_load_dwordx2 v[172:173], v[142:143], off offset:-2560
	s_and_b64 vcc, exec, s[0:1]
	s_cbranch_vccnz .LBB0_5412
	global_load_dwordx2 v[144:145], v[164:165], off offset:-2048
	s_mov_b64 s[8:9], 0
.LBB0_5412:
	s_andn2_b64 vcc, exec, s[8:9]
	s_cbranch_vccnz .LBB0_5414
	global_load_dwordx4 v[142:145], v[178:179], off offset:3072
.LBB0_5414:
	v_add_co_u32_e32 v146, vcc, 0xf7e00000, v164
	s_mov_b64 s[8:9], -1
	s_nop 0
	v_addc_co_u32_e32 v147, vcc, -1, v165, vcc
	global_load_dwordx2 v[174:175], v[146:147], off offset:-2048
	s_and_b64 vcc, exec, s[0:1]
	s_cbranch_vccnz .LBB0_5416
	global_load_dwordx2 v[148:149], v[164:165], off offset:-1536
	s_mov_b64 s[8:9], 0
.LBB0_5416:
	s_andn2_b64 vcc, exec, s[8:9]
	s_cbranch_vccnz .LBB0_5418
	v_add_co_u32_e32 v146, vcc, 0x1000, v178
	s_nop 1
	v_addc_co_u32_e32 v147, vcc, 0, v179, vcc
	global_load_dwordx4 v[146:149], v[146:147], off
.LBB0_5418:
	v_add_co_u32_e32 v150, vcc, 0xf7e00000, v164
	s_mov_b64 s[8:9], -1
	s_nop 0
	v_addc_co_u32_e32 v151, vcc, -1, v165, vcc
	global_load_dwordx2 v[176:177], v[150:151], off offset:-1536
	s_and_b64 vcc, exec, s[0:1]
	s_cbranch_vccnz .LBB0_5420
	global_load_dwordx2 v[152:153], v[164:165], off offset:-1024
	s_mov_b64 s[8:9], 0
.LBB0_5420:
	s_andn2_b64 vcc, exec, s[8:9]
	s_cbranch_vccnz .LBB0_5422
	v_add_co_u32_e32 v150, vcc, 0x1000, v178
	s_nop 1
	v_addc_co_u32_e32 v151, vcc, 0, v179, vcc
	global_load_dwordx4 v[150:153], v[150:151], off offset:1024
.LBB0_5422:
	v_add_co_u32_e32 v154, vcc, 0xf7e00000, v164
	s_mov_b64 s[8:9], -1
	s_nop 0
	v_addc_co_u32_e32 v155, vcc, -1, v165, vcc
	global_load_dwordx2 v[180:181], v[154:155], off offset:-1024
	s_and_b64 vcc, exec, s[0:1]
	s_cbranch_vccnz .LBB0_5424
	global_load_dwordx2 v[156:157], v[164:165], off offset:-512
	s_mov_b64 s[8:9], 0
.LBB0_5424:
	s_andn2_b64 vcc, exec, s[8:9]
	s_cbranch_vccnz .LBB0_5426
	v_add_co_u32_e32 v154, vcc, 0x1000, v178
	s_nop 1
	v_addc_co_u32_e32 v155, vcc, 0, v179, vcc
	global_load_dwordx4 v[154:157], v[154:155], off offset:2048
.LBB0_5426:
	v_add_co_u32_e32 v158, vcc, 0xf7e00000, v164
	s_nop 1
	v_addc_co_u32_e32 v159, vcc, -1, v165, vcc
	global_load_dwordx2 v[184:185], v[158:159], off offset:-512
	s_and_b64 vcc, exec, s[0:1]
	s_mov_b64 s[0:1], -1
	s_cbranch_vccnz .LBB0_5428
	global_load_dwordx2 v[160:161], v[164:165], off
	s_mov_b64 s[0:1], 0
.LBB0_5428:
	s_andn2_b64 vcc, exec, s[0:1]
	s_cbranch_vccnz .LBB0_5430
	v_add_co_u32_e32 v158, vcc, 0x1000, v178
	s_nop 1
	v_addc_co_u32_e32 v159, vcc, 0, v179, vcc
	global_load_dwordx4 v[158:161], v[158:159], off offset:3072

; __global__ void __launch_bounds__(512, 2) hse_fwd(Params P) {
	.amdhsa_kernel _Z7hse_fwd6Params
		.amdhsa_group_segment_fixed_size 0
		.amdhsa_private_segment_fixed_size 0
		.amdhsa_kernarg_size 536
		.amdhsa_user_sgpr_count 2
		.amdhsa_user_sgpr_dispatch_ptr 0
		.amdhsa_user_sgpr_queue_ptr 0
		.amdhsa_user_sgpr_kernarg_segment_ptr 1
		.amdhsa_user_sgpr_dispatch_id 0
		.amdhsa_user_sgpr_kernarg_preload_length 0
		.amdhsa_user_sgpr_kernarg_preload_offset 0
		.amdhsa_user_sgpr_private_segment_size 0
		.amdhsa_uses_dynamic_stack 0
		.amdhsa_enable_private_segment 0
		.amdhsa_system_sgpr_workgroup_id_x 1
		.amdhsa_system_sgpr_workgroup_id_y 0
		.amdhsa_system_sgpr_workgroup_id_z 0
		.amdhsa_system_sgpr_workgroup_info 0
		.amdhsa_system_vgpr_workitem_id 0
		.amdhsa_next_free_vgpr 256
		.amdhsa_next_free_sgpr 102
		.amdhsa_accum_offset 256
		.amdhsa_reserve_vcc 1
		.amdhsa_float_round_mode_32 0
		.amdhsa_float_round_mode_16_64 0
		.amdhsa_float_denorm_mode_32 3
		.amdhsa_float_denorm_mode_16_64 3
		.amdhsa_dx10_clamp 1
		.amdhsa_ieee_mode 1
		.amdhsa_fp16_overflow 0
		.amdhsa_tg_split 0
		.amdhsa_exception_fp_ieee_invalid_op 0
		.amdhsa_exception_fp_denorm_src 0
		.amdhsa_exception_fp_ieee_div_zero 0
		.amdhsa_exception_fp_ieee_overflow 0
		.amdhsa_exception_fp_ieee_underflow 0
		.amdhsa_exception_fp_ieee_inexact 0
		.amdhsa_exception_int_div_zero 0
	.end_amdhsa_kernel

; __global__ void __launch_bounds__(512, 2) hse_fwd(Params P) {
amdhsa.kernels:
  - .agpr_count:     0
    .args:
      - .offset:         0
        .size:           280
        .value_kind:     by_value
      - .offset:         280
        .size:           4
        .value_kind:     hidden_block_count_x
      - .offset:         284
        .size:           4
        .value_kind:     hidden_block_count_y
      - .offset:         288
        .size:           4
        .value_kind:     hidden_block_count_z
      - .offset:         292
        .size:           2
        .value_kind:     hidden_group_size_x
      - .offset:         294
        .size:           2
        .value_kind:     hidden_group_size_y
      - .offset:         296
        .size:           2
        .value_kind:     hidden_group_size_z
      - .offset:         298
        .size:           2
        .value_kind:     hidden_remainder_x
      - .offset:         300
        .size:           2
        .value_kind:     hidden_remainder_y
      - .offset:         302
        .size:           2
        .value_kind:     hidden_remainder_z
      - .offset:         320
        .size:           8
        .value_kind:     hidden_global_offset_x
      - .offset:         328
        .size:           8
        .value_kind:     hidden_global_offset_y
      - .offset:         336
        .size:           8
        .value_kind:     hidden_global_offset_z
      - .offset:         344
        .size:           2
        .value_kind:     hidden_grid_dims
      - .offset:         400
        .size:           4
        .value_kind:     hidden_dynamic_lds_size
    .group_segment_fixed_size: 0
    .kernarg_segment_align: 8
    .kernarg_segment_size: 536
    .language:       OpenCL C
    .language_version:
      - 2
      - 0
    .max_flat_workgroup_size: 512
    .name:           _Z7hse_fwd6Params
    .private_segment_fixed_size: 0
    .sgpr_count:     108
    .sgpr_spill_count: 217
    .symbol:         _Z7hse_fwd6Params.kd
    .uniform_work_group_size: 1
    .uses_dynamic_stack: false
    .vgpr_count:     256
    .vgpr_spill_count: 0
    .wavefront_size: 64
